# v34 + nt on the ffn_norm phase's x1 row loads
# speedup vs baseline: 1.0063x; 1.0063x over previous
; __device__ __forceinline__ unsigned pk2(float lo, float hi) { f32v2_t v = {lo, hi}; bf16v2_t r = __builtin_convertvector(v, bf16v2_t); return __builtin_bit_cast(unsigned, r); }
; __device__ void phase_ffn_norm(const Params& p) {
;     ...
;   for (int t = gw; t < T; t += nw) {
;     const float* x = x1 + (size_t)t * DM;
;     f32x4 v[4]; float ss = 0.f;
; #pragma unroll
;     for (int i = 0; i < 4; ++i) { v[i] = *(const f32x4*)(x + i * 256 + lane * 4); ss += v[i][0] * v[i][0] + v[i][1] * v[i][1] + v[i][2] * v[i][2] + v[i][3] * v[i][3]; }
;     ss = wave_sum(ss);
;     const float rs = rsqrtf(ss * (1.f / DM) + EPS);
; #pragma unroll
;     for (int i = 0; i < 4; ++i) {
;       f32x4 gg = *(const f32x4*)(g + i * 256 + lane * 4);
;       u32x2 w; w.x = pk2(v[i][0] * rs * gg[0], v[i][1] * rs * gg[1]); w.y = pk2(v[i][2] * rs * gg[2], v[i][3] * rs * gg[3]);
;       *(u32x2*)(hf + (size_t)t * LDH + i * 256 + lane * 4) = w;
;     }
.LBB0_945:
	v_lshl_add_u64 v[0:1], s[96:97], 0, v[34:35]
	v_add_co_u32_e32 v4, vcc, 0xa08e000, v0
	s_mov_b32 s44, 0x800000
	s_nop 0
	v_addc_co_u32_e32 v5, vcc, 0, v1, vcc
	global_load_dwordx4 v[52:55], v[4:5], off nt
	global_load_dwordx4 v[0:3], v[4:5], off offset:1024 nt
	global_load_dwordx4 v[8:11], v[4:5], off offset:2048 nt
	global_load_dwordx4 v[4:7], v[4:5], off offset:3072 nt
	v_add_u32_e32 v50, s27, v50
	v_lshl_add_u64 v[34:35], v[34:35], 0, s[18:19]
	s_waitcnt vmcnt(2)
	v_mov_b32_e32 v74, v53
	v_mov_b32_e32 v75, v1
	v_mov_b32_e32 v76, v52
	v_mov_b32_e32 v77, v0
	v_pk_mul_f32 v[74:75], v[74:75], v[74:75]
	s_nop 0
	v_pk_fma_f32 v[76:77], v[76:77], v[76:77], v[74:75]
	v_mov_b32_e32 v74, v54
	v_mov_b32_e32 v75, v2
	v_pk_fma_f32 v[76:77], v[74:75], v[74:75], v[76:77]
	v_mov_b32_e32 v74, v55
	v_mov_b32_e32 v75, v3
	v_pk_fma_f32 v[56:57], v[74:75], v[74:75], v[76:77]
	s_nop 0
	v_add_f32_e32 v14, v56, v57
	s_waitcnt vmcnt(1)
	v_mov_b32_e32 v60, v9
	s_waitcnt vmcnt(0)
	v_mov_b32_e32 v61, v5
	v_mov_b32_e32 v58, v8
	v_mov_b32_e32 v59, v4
	v_pk_mul_f32 v[60:61], v[60:61], v[60:61]
	s_nop 0
	v_pk_fma_f32 v[58:59], v[58:59], v[58:59], v[60:61]
	v_mov_b32_e32 v60, v10
	v_mov_b32_e32 v61, v6
	v_pk_fma_f32 v[58:59], v[60:61], v[60:61], v[58:59]
	v_mov_b32_e32 v60, v11
	v_mov_b32_e32 v61, v7
	v_pk_fma_f32 v[58:59], v[60:61], v[60:61], v[58:59]
	v_lshl_add_u64 v[60:61], s[96:97], 0, v[36:37]
	v_add_f32_e32 v14, v14, v58
	v_add_f32_e32 v14, v14, v59
	ds_bpermute_b32 v51, v29, v14
	v_lshl_add_u64 v[36:37], v[36:37], 0, s[40:41]
	s_waitcnt lgkmcnt(0)
	v_add_f32_e32 v14, v14, v51
	ds_bpermute_b32 v51, v31, v14
	s_waitcnt lgkmcnt(0)
	v_add_f32_e32 v14, v14, v51
	ds_bpermute_b32 v51, v33, v14
	s_waitcnt lgkmcnt(0)
	v_add_f32_e32 v14, v14, v51
	ds_bpermute_b32 v51, v47, v14
	s_waitcnt lgkmcnt(0)
	v_add_f32_e32 v14, v14, v51
	ds_bpermute_b32 v51, v48, v14
	s_waitcnt lgkmcnt(0)
	v_add_f32_e32 v14, v14, v51
	ds_bpermute_b32 v51, v49, v14
	s_waitcnt lgkmcnt(0)
	v_add_f32_e32 v14, v14, v51
	v_fmamk_f32 v14, v14, 0x3a800000, v38
	v_cmp_gt_f32_e32 vcc, s44, v14
	v_mul_f32_e32 v51, 0x4b800000, v14
	s_mov_b32 s44, 0x5b7e000
	v_cndmask_b32_e32 v14, v14, v51, vcc
	v_rsq_f32_e32 v14, v14
	s_nop 0
	v_mul_f32_e32 v51, 0x45800000, v14
	v_cndmask_b32_e32 v14, v14, v51, vcc
	v_pk_mul_f32 v[52:53], v[52:53], v[14:15] op_sel_hi:[1,0]
	v_pk_mul_f32 v[54:55], v[54:55], v[14:15] op_sel_hi:[1,0]
	v_pk_mul_f32 v[0:1], v[0:1], v[14:15] op_sel_hi:[1,0]
	v_pk_mul_f32 v[2:3], v[2:3], v[14:15] op_sel_hi:[1,0]
	v_pk_mul_f32 v[8:9], v[8:9], v[14:15] op_sel_hi:[1,0]
	v_pk_mul_f32 v[4:5], v[4:5], v[14:15] op_sel_hi:[1,0]
	v_pk_mul_f32 v[10:11], v[10:11], v[14:15] op_sel_hi:[1,0]
	v_pk_mul_f32 v[6:7], v[6:7], v[14:15] op_sel_hi:[1,0]
	v_pk_mul_f32 v[52:53], v[100:101], v[52:53]
	v_pk_mul_f32 v[54:55], v[102:103], v[54:55]
	v_add_co_u32_e32 v56, vcc, s44, v60
	v_cvt_pk_bf16_f32 v52, v52, v53
	v_cvt_pk_bf16_f32 v53, v54, v55
	v_addc_co_u32_e32 v57, vcc, 0, v61, vcc
	global_store_dwordx2 v[56:57], v[52:53], off
	s_mov_b32 s44, 0x81ff
	v_cmp_lt_i32_e32 vcc, s44, v50
	s_or_b64 s[2:3], vcc, s[2:3]
	v_pk_mul_f32 v[0:1], v[104:105], v[0:1]
	v_pk_mul_f32 v[2:3], v[106:107], v[2:3]
	v_pk_mul_f32 v[8:9], v[108:109], v[8:9]
	v_pk_mul_f32 v[10:11], v[110:111], v[10:11]
	v_cvt_pk_bf16_f32 v0, v0, v1
	v_cvt_pk_bf16_f32 v1, v2, v3
	global_store_dwordx2 v[56:57], v[0:1], off offset:512
	v_pk_mul_f32 v[4:5], v[112:113], v[4:5]
	v_pk_mul_f32 v[6:7], v[114:115], v[6:7]
	v_cvt_pk_bf16_f32 v8, v8, v9
	v_cvt_pk_bf16_f32 v9, v10, v11
	global_store_dwordx2 v[56:57], v[8:9], off offset:1024
	v_cvt_pk_bf16_f32 v4, v4, v5
	v_cvt_pk_bf16_f32 v5, v6, v7
	global_store_dwordx2 v[56:57], v[4:5], off offset:1536
	s_andn2_b64 exec, exec, s[2:3]
	s_cbranch_execnz .LBB0_945
